# SwiGLU epilogues: scalar g*c and 1+e pairs packed into v_pk_mul_f32 / v_pk_add_f32 (62 fewer VALU per epilogue), same f32 math
# baseline (speedup 1.0000x reference)
.LBB0_173:
	v_mov_b32_e32 v254, 1.0
	v_lshl_add_u32 v202, s20, 8, v1
	s_and_b32 s71, s55, 1
	s_lshl_b32 s71, s71, 12
	s_add_i32 s71, s71, 0x20000
	v_lshl_add_u32 v206, v1, 4, s71
	v_or_b32_e32 v162, 16, v202
	v_ashrrev_i32_e32 v203, 31, v202
	v_ashrrev_i32_e32 v163, 31, v162
	v_or_b32_e32 v160, 32, v202
	v_or_b32_e32 v158, 48, v202
	v_ashrrev_i32_e32 v161, 31, v160
	v_ashrrev_i32_e32 v159, 31, v158
	v_add_u32_e32 v156, 0x80, v202
	v_add_u32_e32 v154, 0x90, v202
	ds_read_b128 v[170:173], v206
	ds_read_b128 v[174:177], v206 offset:256
	v_ashrrev_i32_e32 v157, 31, v156
	v_ashrrev_i32_e32 v155, 31, v154
	ds_read_b128 v[178:181], v206 offset:512
	ds_read_b128 v[182:185], v206 offset:768
	ds_read_b128 v[186:189], v206 offset:2048
	ds_read_b128 v[190:193], v206 offset:2304
	v_add_u32_e32 v150, 0xa0, v202
	v_ashrrev_i32_e32 v151, 31, v150
	ds_read_b128 v[194:197], v206 offset:2560
	v_add_u32_e32 v148, 0xb0, v202
	v_ashrrev_i32_e32 v149, 31, v148
	ds_read_b128 v[198:201], v206 offset:2816
	v_pk_mul_f32 v[124:125], v[128:129], v[124:125]
	v_pk_mul_f32 v[122:123], v[126:127], v[122:123]
	v_pk_mul_f32 v[116:117], v[120:121], v[116:117]
	v_lshl_or_b32 v204, s68, 7, v164
	v_pk_mul_f32 v[114:115], v[118:119], v[114:115]
	v_ashrrev_i32_e32 v205, 31, v204
	v_pk_mul_f32 v[108:109], v[112:113], v[108:109]
	v_pk_mul_f32 v[106:107], v[110:111], v[106:107]
	v_pk_mul_f32 v[100:101], v[104:105], v[100:101]
	v_pk_mul_f32 v[98:99], v[102:103], v[98:99]
	v_pk_mul_f32 v[92:93], v[96:97], v[92:93]
	v_pk_mul_f32 v[90:91], v[94:95], v[90:91]
	v_pk_mul_f32 v[84:85], v[88:89], v[84:85]
	v_pk_mul_f32 v[82:83], v[86:87], v[82:83]
	v_pk_mul_f32 v[76:77], v[80:81], v[76:77]
	v_pk_mul_f32 v[74:75], v[78:79], v[74:75]
	v_pk_mul_f32 v[68:69], v[72:73], v[68:69]
	v_pk_mul_f32 v[66:67], v[70:71], v[66:67]
	v_pk_mul_f32 v[60:61], v[64:65], v[60:61]
	v_pk_mul_f32 v[58:59], v[62:63], v[58:59]
	v_pk_mul_f32 v[52:53], v[56:57], v[52:53]
	v_pk_mul_f32 v[50:51], v[54:55], v[50:51]
	v_pk_mul_f32 v[44:45], v[48:49], v[44:45]
	v_pk_mul_f32 v[42:43], v[46:47], v[42:43]
	v_pk_mul_f32 v[36:37], v[40:41], v[36:37]
	v_pk_mul_f32 v[34:35], v[38:39], v[34:35]
	v_pk_mul_f32 v[28:29], v[32:33], v[28:29]
	v_pk_mul_f32 v[26:27], v[30:31], v[26:27]
	v_pk_mul_f32 v[20:21], v[24:25], v[20:21]
	v_pk_mul_f32 v[18:19], v[22:23], v[18:19]
	v_pk_mul_f32 v[12:13], v[16:17], v[12:13]
	v_pk_mul_f32 v[10:11], v[14:15], v[10:11]
	v_pk_mul_f32 v[4:5], v[8:9], v[4:5]
	v_pk_mul_f32 v[2:3], v[6:7], v[2:3]
	s_andn2_b64 vcc, exec, s[2:3]
	s_mov_b64 s[2:3], -1
	v_readlane_b32 s70, v253, 14
	v_readlane_b32 s71, v253, 15
	s_waitcnt lgkmcnt(0)
	v_mov_b32_e32 v152, v171
	v_mov_b32_e32 v153, v172
	v_mov_b32_e32 v171, v173
	v_pk_add_f32 v[152:153], v[152:153], v[170:171]
	v_mov_b32_e32 v170, v175
	v_add_f32_e32 v149, v152, v153
	v_fmamk_f32 v149, v149, 0x3a800000, v168
	v_mov_b32_e32 v171, v176
	v_mov_b32_e32 v175, v177
	v_mov_b32_e32 v172, v179
	v_mov_b32_e32 v173, v180
	v_mov_b32_e32 v179, v181
	v_mov_b32_e32 v176, v183
	v_mov_b32_e32 v177, v184
	v_mov_b32_e32 v183, v185
	v_mov_b32_e32 v180, v187
	v_mov_b32_e32 v181, v188
	v_mov_b32_e32 v187, v189
	v_mov_b32_e32 v184, v191
	v_mov_b32_e32 v185, v192
	v_mov_b32_e32 v191, v193
	v_mov_b32_e32 v188, v195
	v_mov_b32_e32 v189, v196
	v_mov_b32_e32 v195, v197
	v_rsq_f32_e32 v163, v149
	v_mov_b32_e32 v192, v199
	v_mov_b32_e32 v193, v200
	v_mov_b32_e32 v199, v201
	v_pk_add_f32 v[152:153], v[170:171], v[174:175]
	v_pk_add_f32 v[170:171], v[172:173], v[178:179]
	v_pk_add_f32 v[172:173], v[176:177], v[182:183]
	v_pk_add_f32 v[174:175], v[180:181], v[186:187]
	v_pk_add_f32 v[176:177], v[184:185], v[190:191]
	v_pk_add_f32 v[178:179], v[188:189], v[194:195]
	v_pk_add_f32 v[180:181], v[192:193], v[198:199]
	v_add_f32_e32 v151, v152, v153
	v_add_f32_e32 v152, v170, v171
	v_add_f32_e32 v153, v172, v173
	v_add_f32_e32 v155, v174, v175
	v_add_f32_e32 v157, v176, v177
	v_add_f32_e32 v159, v178, v179
	v_add_f32_e32 v161, v180, v181
	v_fmamk_f32 v149, v151, 0x3a800000, v168
	v_fmamk_f32 v151, v152, 0x3a800000, v168
	v_fmamk_f32 v152, v153, 0x3a800000, v168
	v_fmamk_f32 v153, v155, 0x3a800000, v168
	v_fmamk_f32 v155, v157, 0x3a800000, v168
	v_fmamk_f32 v157, v159, 0x3a800000, v168
	v_fmamk_f32 v159, v161, 0x3a800000, v168
	v_rsq_f32_e32 v169, v151
	v_rsq_f32_e32 v151, v157
	v_mul_f32_e32 v157, 0xbfb8aa3b, v163
	v_rsq_f32_e32 v161, v149
	v_rsq_f32_e32 v149, v159
	v_pk_mul_f32 v[174:175], v[126:127], v[156:157] op_sel:[0,1] op_sel_hi:[1,1]
	v_exp_f32_e32 v174, v174
	v_exp_f32_e32 v175, v175
	v_mul_f32_e32 v172, v163, v163
	v_pk_add_f32 v[174:175], v[174:175], v[254:255] op_sel_hi:[1,0]
	v_rcp_f32_e32 v174, v174
	v_rcp_f32_e32 v175, v175
	v_pk_mul_f32 v[128:129], v[128:129], v[156:157] op_sel:[0,1] op_sel_hi:[1,1]
	v_exp_f32_e32 v128, v128
	v_exp_f32_e32 v129, v129
	v_rsq_f32_e32 v173, v152
	v_rsq_f32_e32 v176, v153
	v_pk_add_f32 v[128:129], v[128:129], v[254:255] op_sel_hi:[1,0]
	v_rcp_f32_e32 v128, v128
	v_rcp_f32_e32 v129, v129
	v_pk_mul_f32 v[126:127], v[172:173], v[174:175] op_sel_hi:[0,1]
	v_pk_mul_f32 v[122:123], v[122:123], v[126:127]
	v_mov_b64_e32 v[152:153], s[4:5]
	v_pk_mul_f32 v[126:127], v[172:173], v[128:129] op_sel_hi:[0,1]
	v_pk_mul_f32 v[128:129], v[118:119], v[156:157] op_sel:[0,1] op_sel_hi:[1,1]
	v_exp_f32_e32 v128, v128
	v_exp_f32_e32 v129, v129
	v_pk_mul_f32 v[124:125], v[124:125], v[126:127]
	v_mad_i64_i32 v[170:171], s[28:29], v202, s67, v[152:153]
	v_pk_add_f32 v[126:127], v[128:129], v[254:255] op_sel_hi:[1,0]
	v_mul_f32_e32 v128, v120, v157
	v_mul_f32_e32 v129, v121, v157
	v_exp_f32_e32 v128, v128
	v_exp_f32_e32 v129, v129
	v_rcp_f32_e32 v126, v126
	v_rcp_f32_e32 v127, v127
	v_add_f32_e32 v120, 1.0, v128
	v_add_f32_e32 v121, 1.0, v129
	v_rcp_f32_e32 v120, v120
	v_rcp_f32_e32 v121, v121
	v_pk_mul_f32 v[118:119], v[172:173], v[126:127] op_sel_hi:[0,1]
	v_pk_mul_f32 v[118:119], v[114:115], v[118:119]
	v_rsq_f32_e32 v155, v155
	v_pk_mul_f32 v[114:115], v[172:173], v[120:121] op_sel_hi:[0,1]
	v_pk_mul_f32 v[120:121], v[116:117], v[114:115]
	v_lshlrev_b64 v[114:115], 1, v[204:205]
	v_lshl_add_u64 v[126:127], v[170:171], 0, v[114:115]
	v_cvt_pk_bf16_f32 v116, v122, v123
	v_cvt_pk_bf16_f32 v117, v124, v125
	v_cvt_pk_bf16_f32 v118, v118, v119
	v_cvt_pk_bf16_f32 v119, v120, v121
	global_store_dwordx4 v[126:127], v[116:119], off
	s_nop 1
	v_mul_f32_e32 v119, 0xbfb8aa3b, v161
	v_pk_mul_f32 v[120:121], v[110:111], v[118:119] op_sel:[0,1] op_sel_hi:[1,1]
	v_exp_f32_e32 v120, v120
	v_exp_f32_e32 v121, v121
	v_pk_mul_f32 v[122:123], v[112:113], v[118:119] op_sel:[0,1] op_sel_hi:[1,1]
	v_exp_f32_e32 v122, v122
	v_exp_f32_e32 v123, v123
	v_pk_add_f32 v[120:121], v[120:121], v[254:255] op_sel_hi:[1,0]
	v_rcp_f32_e32 v120, v120
	v_rcp_f32_e32 v121, v121
	v_pk_add_f32 v[122:123], v[122:123], v[254:255] op_sel_hi:[1,0]
	v_rcp_f32_e32 v112, v122
	v_rcp_f32_e32 v113, v123
	v_mul_f32_e32 v118, v161, v161
	v_pk_mul_f32 v[110:111], v[118:119], v[120:121] op_sel_hi:[0,1]
	v_pk_mul_f32 v[106:107], v[106:107], v[110:111]
	v_pk_mul_f32 v[110:111], v[118:119], v[112:113] op_sel_hi:[0,1]
	v_pk_mul_f32 v[112:113], v[102:103], v[118:119] op_sel:[0,1] op_sel_hi:[1,1]
	v_exp_f32_e32 v112, v112
	v_exp_f32_e32 v113, v113
	v_pk_mul_f32 v[108:109], v[108:109], v[110:111]
	v_mad_i64_i32 v[116:117], s[28:29], v162, s67, v[152:153]
	v_pk_add_f32 v[110:111], v[112:113], v[254:255] op_sel_hi:[1,0]
	v_pk_mul_f32 v[112:113], v[104:105], v[118:119] op_sel:[0,1] op_sel_hi:[1,1]
	v_exp_f32_e32 v112, v112
	v_exp_f32_e32 v113, v113
	v_rcp_f32_e32 v110, v110
	v_rcp_f32_e32 v111, v111
	v_pk_add_f32 v[112:113], v[112:113], v[254:255] op_sel_hi:[1,0]
	v_rcp_f32_e32 v104, v112
	v_rcp_f32_e32 v105, v113
	v_pk_mul_f32 v[102:103], v[118:119], v[110:111] op_sel_hi:[0,1]
	v_pk_mul_f32 v[102:103], v[98:99], v[102:103]
	v_lshl_add_u64 v[110:111], v[116:117], 0, v[114:115]
	v_pk_mul_f32 v[98:99], v[118:119], v[104:105] op_sel_hi:[0,1]
	v_pk_mul_f32 v[104:105], v[100:101], v[98:99]
	v_cvt_pk_bf16_f32 v98, v106, v107
	v_cvt_pk_bf16_f32 v99, v108, v109
	v_cvt_pk_bf16_f32 v100, v102, v103
	v_cvt_pk_bf16_f32 v101, v104, v105
	global_store_dwordx4 v[110:111], v[98:101], off
	s_nop 1
	v_mul_f32_e32 v101, 0xbfb8aa3b, v169
	v_pk_mul_f32 v[102:103], v[94:95], v[100:101] op_sel:[0,1] op_sel_hi:[1,1]
	v_exp_f32_e32 v102, v102
	v_exp_f32_e32 v103, v103
	v_pk_mul_f32 v[104:105], v[96:97], v[100:101] op_sel:[0,1] op_sel_hi:[1,1]
	v_exp_f32_e32 v104, v104
	v_exp_f32_e32 v105, v105
	v_pk_add_f32 v[102:103], v[102:103], v[254:255] op_sel_hi:[1,0]
	v_rcp_f32_e32 v102, v102
	v_rcp_f32_e32 v103, v103
	v_pk_add_f32 v[104:105], v[104:105], v[254:255] op_sel_hi:[1,0]
	v_rcp_f32_e32 v96, v104
	v_rcp_f32_e32 v97, v105
	v_mul_f32_e32 v100, v169, v169
	v_pk_mul_f32 v[94:95], v[100:101], v[102:103] op_sel_hi:[0,1]
	v_pk_mul_f32 v[90:91], v[90:91], v[94:95]
	v_pk_mul_f32 v[94:95], v[100:101], v[96:97] op_sel_hi:[0,1]
	v_pk_mul_f32 v[96:97], v[86:87], v[100:101] op_sel:[0,1] op_sel_hi:[1,1]
	v_exp_f32_e32 v96, v96
	v_exp_f32_e32 v97, v97
	v_pk_mul_f32 v[92:93], v[92:93], v[94:95]
	v_mad_i64_i32 v[98:99], s[28:29], v160, s67, v[152:153]
	v_pk_add_f32 v[94:95], v[96:97], v[254:255] op_sel_hi:[1,0]
	v_pk_mul_f32 v[96:97], v[88:89], v[100:101] op_sel:[0,1] op_sel_hi:[1,1]
	v_exp_f32_e32 v96, v96
	v_exp_f32_e32 v97, v97
	v_rcp_f32_e32 v94, v94
	v_rcp_f32_e32 v95, v95
	v_pk_add_f32 v[96:97], v[96:97], v[254:255] op_sel_hi:[1,0]
	v_rcp_f32_e32 v88, v96
	v_rcp_f32_e32 v89, v97
	v_pk_mul_f32 v[86:87], v[100:101], v[94:95] op_sel_hi:[0,1]
	v_pk_mul_f32 v[86:87], v[82:83], v[86:87]
	v_lshl_add_u64 v[94:95], v[98:99], 0, v[114:115]
	v_pk_mul_f32 v[82:83], v[100:101], v[88:89] op_sel_hi:[0,1]
	v_pk_mul_f32 v[88:89], v[84:85], v[82:83]
	v_cvt_pk_bf16_f32 v82, v90, v91
	v_cvt_pk_bf16_f32 v83, v92, v93
	v_cvt_pk_bf16_f32 v84, v86, v87
	v_cvt_pk_bf16_f32 v85, v88, v89
	global_store_dwordx4 v[94:95], v[82:85], off
	s_nop 1
	v_mul_f32_e32 v85, 0xbfb8aa3b, v173
	v_pk_mul_f32 v[86:87], v[78:79], v[84:85] op_sel:[0,1] op_sel_hi:[1,1]
	v_exp_f32_e32 v86, v86
	v_exp_f32_e32 v87, v87
	v_pk_mul_f32 v[88:89], v[80:81], v[84:85] op_sel:[0,1] op_sel_hi:[1,1]
	v_exp_f32_e32 v88, v88
	v_exp_f32_e32 v89, v89
	v_pk_add_f32 v[86:87], v[86:87], v[254:255] op_sel_hi:[1,0]
	v_rcp_f32_e32 v86, v86
	v_rcp_f32_e32 v87, v87
	v_pk_add_f32 v[88:89], v[88:89], v[254:255] op_sel_hi:[1,0]
	v_rcp_f32_e32 v80, v88
	v_rcp_f32_e32 v81, v89
	v_mul_f32_e32 v84, v173, v173
	v_pk_mul_f32 v[78:79], v[84:85], v[86:87] op_sel_hi:[0,1]
	v_pk_mul_f32 v[74:75], v[74:75], v[78:79]
	v_pk_mul_f32 v[78:79], v[84:85], v[80:81] op_sel_hi:[0,1]
	v_pk_mul_f32 v[80:81], v[70:71], v[84:85] op_sel:[0,1] op_sel_hi:[1,1]
	v_exp_f32_e32 v80, v80
	v_exp_f32_e32 v81, v81
	v_pk_mul_f32 v[76:77], v[76:77], v[78:79]
	v_mad_i64_i32 v[82:83], s[28:29], v158, s67, v[152:153]
	v_pk_add_f32 v[78:79], v[80:81], v[254:255] op_sel_hi:[1,0]
	v_pk_mul_f32 v[80:81], v[72:73], v[84:85] op_sel:[0,1] op_sel_hi:[1,1]
	v_exp_f32_e32 v80, v80
	v_exp_f32_e32 v81, v81
	v_rcp_f32_e32 v78, v78
	v_rcp_f32_e32 v79, v79
	v_pk_add_f32 v[80:81], v[80:81], v[254:255] op_sel_hi:[1,0]
	v_rcp_f32_e32 v72, v80
	v_rcp_f32_e32 v73, v81
	v_pk_mul_f32 v[70:71], v[84:85], v[78:79] op_sel_hi:[0,1]
	v_pk_mul_f32 v[70:71], v[66:67], v[70:71]
	v_lshl_add_u64 v[78:79], v[82:83], 0, v[114:115]
	v_pk_mul_f32 v[66:67], v[84:85], v[72:73] op_sel_hi:[0,1]
	v_pk_mul_f32 v[72:73], v[68:69], v[66:67]
	v_cvt_pk_bf16_f32 v66, v74, v75
	v_cvt_pk_bf16_f32 v67, v76, v77
	v_cvt_pk_bf16_f32 v68, v70, v71
	v_cvt_pk_bf16_f32 v69, v72, v73
	global_store_dwordx4 v[78:79], v[66:69], off
	s_nop 1
	v_mul_f32_e32 v69, 0xbfb8aa3b, v176
	v_pk_mul_f32 v[70:71], v[62:63], v[68:69] op_sel:[0,1] op_sel_hi:[1,1]
	v_exp_f32_e32 v70, v70
	v_exp_f32_e32 v71, v71
	v_pk_mul_f32 v[72:73], v[64:65], v[68:69] op_sel:[0,1] op_sel_hi:[1,1]
	v_exp_f32_e32 v72, v72
	v_exp_f32_e32 v73, v73
	v_pk_add_f32 v[70:71], v[70:71], v[254:255] op_sel_hi:[1,0]
	v_rcp_f32_e32 v70, v70
	v_rcp_f32_e32 v71, v71
	v_pk_add_f32 v[72:73], v[72:73], v[254:255] op_sel_hi:[1,0]
	v_rcp_f32_e32 v64, v72
	v_rcp_f32_e32 v65, v73
	v_mul_f32_e32 v68, v176, v176
	v_pk_mul_f32 v[62:63], v[68:69], v[70:71] op_sel_hi:[0,1]
	v_pk_mul_f32 v[58:59], v[58:59], v[62:63]
	v_pk_mul_f32 v[62:63], v[68:69], v[64:65] op_sel_hi:[0,1]
	v_pk_mul_f32 v[64:65], v[54:55], v[68:69] op_sel:[0,1] op_sel_hi:[1,1]
	v_exp_f32_e32 v64, v64
	v_exp_f32_e32 v65, v65
	v_pk_mul_f32 v[60:61], v[60:61], v[62:63]
	v_mad_i64_i32 v[66:67], s[28:29], v156, s67, v[152:153]
	v_pk_add_f32 v[62:63], v[64:65], v[254:255] op_sel_hi:[1,0]
	v_pk_mul_f32 v[64:65], v[56:57], v[68:69] op_sel:[0,1] op_sel_hi:[1,1]
	v_exp_f32_e32 v64, v64
	v_exp_f32_e32 v65, v65
	v_rcp_f32_e32 v62, v62
	v_rcp_f32_e32 v63, v63
	v_pk_add_f32 v[64:65], v[64:65], v[254:255] op_sel_hi:[1,0]
	v_rcp_f32_e32 v56, v64
	v_rcp_f32_e32 v57, v65
	v_pk_mul_f32 v[54:55], v[68:69], v[62:63] op_sel_hi:[0,1]
	v_pk_mul_f32 v[54:55], v[50:51], v[54:55]
	v_lshl_add_u64 v[62:63], v[66:67], 0, v[114:115]
	v_pk_mul_f32 v[50:51], v[68:69], v[56:57] op_sel_hi:[0,1]
	v_pk_mul_f32 v[56:57], v[52:53], v[50:51]
	v_cvt_pk_bf16_f32 v50, v58, v59
	v_cvt_pk_bf16_f32 v51, v60, v61
	v_cvt_pk_bf16_f32 v52, v54, v55
	v_cvt_pk_bf16_f32 v53, v56, v57
	global_store_dwordx4 v[62:63], v[50:53], off
	s_nop 1
	v_mul_f32_e32 v53, 0xbfb8aa3b, v155
	v_pk_mul_f32 v[54:55], v[46:47], v[52:53] op_sel:[0,1] op_sel_hi:[1,1]
	v_exp_f32_e32 v54, v54
	v_exp_f32_e32 v55, v55
	v_pk_mul_f32 v[56:57], v[48:49], v[52:53] op_sel:[0,1] op_sel_hi:[1,1]
	v_exp_f32_e32 v56, v56
	v_exp_f32_e32 v57, v57
	v_pk_add_f32 v[54:55], v[54:55], v[254:255] op_sel_hi:[1,0]
	v_rcp_f32_e32 v54, v54
	v_rcp_f32_e32 v55, v55
	v_pk_add_f32 v[56:57], v[56:57], v[254:255] op_sel_hi:[1,0]
	v_rcp_f32_e32 v48, v56
	v_rcp_f32_e32 v49, v57
	v_mul_f32_e32 v52, v155, v155
	v_pk_mul_f32 v[46:47], v[52:53], v[54:55] op_sel_hi:[0,1]
	v_pk_mul_f32 v[42:43], v[42:43], v[46:47]
	v_pk_mul_f32 v[46:47], v[52:53], v[48:49] op_sel_hi:[0,1]
	v_pk_mul_f32 v[48:49], v[38:39], v[52:53] op_sel:[0,1] op_sel_hi:[1,1]
	v_exp_f32_e32 v48, v48
	v_exp_f32_e32 v49, v49
	v_pk_mul_f32 v[44:45], v[44:45], v[46:47]
	v_mad_i64_i32 v[50:51], s[28:29], v154, s67, v[152:153]
	v_pk_add_f32 v[46:47], v[48:49], v[254:255] op_sel_hi:[1,0]
	v_pk_mul_f32 v[48:49], v[40:41], v[52:53] op_sel:[0,1] op_sel_hi:[1,1]
	v_exp_f32_e32 v48, v48
	v_exp_f32_e32 v49, v49
	v_rcp_f32_e32 v46, v46
	v_rcp_f32_e32 v47, v47
	v_pk_add_f32 v[48:49], v[48:49], v[254:255] op_sel_hi:[1,0]
	v_rcp_f32_e32 v40, v48
	v_rcp_f32_e32 v41, v49
	v_pk_mul_f32 v[38:39], v[52:53], v[46:47] op_sel_hi:[0,1]
	v_pk_mul_f32 v[38:39], v[34:35], v[38:39]
	v_lshl_add_u64 v[46:47], v[50:51], 0, v[114:115]
	v_pk_mul_f32 v[34:35], v[52:53], v[40:41] op_sel_hi:[0,1]
	v_pk_mul_f32 v[40:41], v[36:37], v[34:35]
	v_cvt_pk_bf16_f32 v34, v42, v43
	v_cvt_pk_bf16_f32 v35, v44, v45
	v_cvt_pk_bf16_f32 v36, v38, v39
	v_cvt_pk_bf16_f32 v37, v40, v41
	global_store_dwordx4 v[46:47], v[34:37], off
	s_nop 1
	v_mul_f32_e32 v37, 0xbfb8aa3b, v151
	v_pk_mul_f32 v[38:39], v[30:31], v[36:37] op_sel:[0,1] op_sel_hi:[1,1]
	v_exp_f32_e32 v38, v38
	v_exp_f32_e32 v39, v39
	v_pk_mul_f32 v[40:41], v[32:33], v[36:37] op_sel:[0,1] op_sel_hi:[1,1]
	v_exp_f32_e32 v40, v40
	v_exp_f32_e32 v41, v41
	v_pk_add_f32 v[38:39], v[38:39], v[254:255] op_sel_hi:[1,0]
	v_rcp_f32_e32 v38, v38
	v_rcp_f32_e32 v39, v39
	v_pk_add_f32 v[40:41], v[40:41], v[254:255] op_sel_hi:[1,0]
	v_rcp_f32_e32 v32, v40
	v_rcp_f32_e32 v33, v41
	v_mul_f32_e32 v36, v151, v151
	v_pk_mul_f32 v[30:31], v[36:37], v[38:39] op_sel_hi:[0,1]
	v_pk_mul_f32 v[26:27], v[26:27], v[30:31]
	v_pk_mul_f32 v[30:31], v[36:37], v[32:33] op_sel_hi:[0,1]
	v_pk_mul_f32 v[32:33], v[22:23], v[36:37] op_sel:[0,1] op_sel_hi:[1,1]
	v_exp_f32_e32 v32, v32
	v_exp_f32_e32 v33, v33
	v_pk_mul_f32 v[28:29], v[28:29], v[30:31]
	v_mad_i64_i32 v[34:35], s[28:29], v150, s67, v[152:153]
	v_pk_add_f32 v[30:31], v[32:33], v[254:255] op_sel_hi:[1,0]
	v_pk_mul_f32 v[32:33], v[24:25], v[36:37] op_sel:[0,1] op_sel_hi:[1,1]
	v_exp_f32_e32 v32, v32
	v_exp_f32_e32 v33, v33
	v_rcp_f32_e32 v30, v30
	v_rcp_f32_e32 v31, v31
	v_pk_add_f32 v[32:33], v[32:33], v[254:255] op_sel_hi:[1,0]
	v_rcp_f32_e32 v24, v32
	v_rcp_f32_e32 v25, v33
	v_pk_mul_f32 v[22:23], v[36:37], v[30:31] op_sel_hi:[0,1]
	v_pk_mul_f32 v[22:23], v[18:19], v[22:23]
	v_lshl_add_u64 v[30:31], v[34:35], 0, v[114:115]
	v_pk_mul_f32 v[18:19], v[36:37], v[24:25] op_sel_hi:[0,1]
	v_pk_mul_f32 v[24:25], v[20:21], v[18:19]
	v_cvt_pk_bf16_f32 v18, v26, v27
	v_cvt_pk_bf16_f32 v19, v28, v29
	v_cvt_pk_bf16_f32 v20, v22, v23
	v_cvt_pk_bf16_f32 v21, v24, v25
	global_store_dwordx4 v[30:31], v[18:21], off
	s_nop 1
	v_mul_f32_e32 v21, 0xbfb8aa3b, v149
	v_pk_mul_f32 v[22:23], v[14:15], v[20:21] op_sel:[0,1] op_sel_hi:[1,1]
	v_exp_f32_e32 v22, v22
	v_exp_f32_e32 v23, v23
	v_pk_mul_f32 v[24:25], v[16:17], v[20:21] op_sel:[0,1] op_sel_hi:[1,1]
	v_exp_f32_e32 v24, v24
	v_exp_f32_e32 v25, v25
	v_pk_add_f32 v[22:23], v[22:23], v[254:255] op_sel_hi:[1,0]
	v_rcp_f32_e32 v22, v22
	v_rcp_f32_e32 v23, v23
	v_pk_add_f32 v[24:25], v[24:25], v[254:255] op_sel_hi:[1,0]
	v_rcp_f32_e32 v16, v24
	v_rcp_f32_e32 v17, v25
	v_mul_f32_e32 v20, v149, v149
	v_pk_mul_f32 v[14:15], v[20:21], v[22:23] op_sel_hi:[0,1]
	v_pk_mul_f32 v[10:11], v[10:11], v[14:15]
	v_pk_mul_f32 v[14:15], v[20:21], v[16:17] op_sel_hi:[0,1]
	v_pk_mul_f32 v[16:17], v[6:7], v[20:21] op_sel:[0,1] op_sel_hi:[1,1]
	v_exp_f32_e32 v16, v16
	v_exp_f32_e32 v17, v17
	v_pk_mul_f32 v[12:13], v[12:13], v[14:15]
	v_mad_i64_i32 v[18:19], s[28:29], v148, s67, v[152:153]
	v_pk_add_f32 v[14:15], v[16:17], v[254:255] op_sel_hi:[1,0]
	v_pk_mul_f32 v[16:17], v[8:9], v[20:21] op_sel:[0,1] op_sel_hi:[1,1]
	v_exp_f32_e32 v16, v16
	v_exp_f32_e32 v17, v17
	v_rcp_f32_e32 v14, v14
	v_rcp_f32_e32 v15, v15
	v_pk_add_f32 v[16:17], v[16:17], v[254:255] op_sel_hi:[1,0]
	v_rcp_f32_e32 v8, v16
	v_rcp_f32_e32 v9, v17
	v_pk_mul_f32 v[6:7], v[20:21], v[14:15] op_sel_hi:[0,1]
	v_pk_mul_f32 v[6:7], v[2:3], v[6:7]
	v_lshl_add_u64 v[14:15], v[18:19], 0, v[114:115]
	v_pk_mul_f32 v[2:3], v[20:21], v[8:9] op_sel_hi:[0,1]
	v_pk_mul_f32 v[8:9], v[4:5], v[2:3]
	v_cvt_pk_bf16_f32 v2, v10, v11
	v_cvt_pk_bf16_f32 v3, v12, v13
	v_cvt_pk_bf16_f32 v4, v6, v7
	v_cvt_pk_bf16_f32 v5, v8, v9
	global_store_dwordx4 v[14:15], v[2:5], off
	s_cbranch_vccnz .LBB0_166
	s_andn2_b64 vcc, exec, s[0:1]
	s_cbranch_vccnz .LBB0_165
	s_barrier
	s_branch .LBB0_165

.LBB0_1923:
	v_mov_b32_e32 v254, 1.0
	v_lshl_add_u32 v202, s56, 8, v1
	s_and_b32 s72, s71, 1
	s_lshl_b32 s72, s72, 12
	s_add_i32 s72, s72, 0x20000
	v_lshl_add_u32 v206, v1, 4, s72
	v_or_b32_e32 v162, 16, v202
	v_ashrrev_i32_e32 v203, 31, v202
	v_ashrrev_i32_e32 v163, 31, v162
	v_or_b32_e32 v160, 32, v202
	v_or_b32_e32 v158, 48, v202
	v_ashrrev_i32_e32 v161, 31, v160
	v_ashrrev_i32_e32 v159, 31, v158
	v_add_u32_e32 v156, 0x80, v202
	v_add_u32_e32 v154, 0x90, v202
	ds_read_b128 v[170:173], v206
	ds_read_b128 v[174:177], v206 offset:256
	v_ashrrev_i32_e32 v157, 31, v156
	v_ashrrev_i32_e32 v155, 31, v154
	ds_read_b128 v[178:181], v206 offset:512
	ds_read_b128 v[182:185], v206 offset:768
	ds_read_b128 v[186:189], v206 offset:2048
	ds_read_b128 v[190:193], v206 offset:2304
	v_add_u32_e32 v150, 0xa0, v202
	v_ashrrev_i32_e32 v151, 31, v150
	ds_read_b128 v[194:197], v206 offset:2560
	v_add_u32_e32 v148, 0xb0, v202
	v_ashrrev_i32_e32 v149, 31, v148
	ds_read_b128 v[198:201], v206 offset:2816
	v_pk_mul_f32 v[124:125], v[128:129], v[124:125]
	v_pk_mul_f32 v[122:123], v[126:127], v[122:123]
	v_pk_mul_f32 v[116:117], v[120:121], v[116:117]
	v_lshl_or_b32 v204, s14, 7, v164
	v_pk_mul_f32 v[114:115], v[118:119], v[114:115]
	v_ashrrev_i32_e32 v205, 31, v204
	v_pk_mul_f32 v[108:109], v[112:113], v[108:109]
	v_pk_mul_f32 v[106:107], v[110:111], v[106:107]
	v_pk_mul_f32 v[100:101], v[104:105], v[100:101]
	v_pk_mul_f32 v[98:99], v[102:103], v[98:99]
	v_pk_mul_f32 v[92:93], v[96:97], v[92:93]
	v_pk_mul_f32 v[90:91], v[94:95], v[90:91]
	v_pk_mul_f32 v[84:85], v[88:89], v[84:85]
	v_pk_mul_f32 v[82:83], v[86:87], v[82:83]
	v_pk_mul_f32 v[76:77], v[80:81], v[76:77]
	v_pk_mul_f32 v[74:75], v[78:79], v[74:75]
	v_pk_mul_f32 v[68:69], v[72:73], v[68:69]
	v_pk_mul_f32 v[66:67], v[70:71], v[66:67]
	v_pk_mul_f32 v[60:61], v[64:65], v[60:61]
	v_pk_mul_f32 v[58:59], v[62:63], v[58:59]
	v_pk_mul_f32 v[52:53], v[56:57], v[52:53]
	v_pk_mul_f32 v[50:51], v[54:55], v[50:51]
	v_pk_mul_f32 v[44:45], v[48:49], v[44:45]
	v_pk_mul_f32 v[42:43], v[46:47], v[42:43]
	v_pk_mul_f32 v[36:37], v[40:41], v[36:37]
	v_pk_mul_f32 v[34:35], v[38:39], v[34:35]
	v_pk_mul_f32 v[28:29], v[32:33], v[28:29]
	v_pk_mul_f32 v[26:27], v[30:31], v[26:27]
	v_pk_mul_f32 v[20:21], v[24:25], v[20:21]
	v_pk_mul_f32 v[18:19], v[22:23], v[18:19]
	v_pk_mul_f32 v[12:13], v[16:17], v[12:13]
	v_pk_mul_f32 v[10:11], v[14:15], v[10:11]
	v_pk_mul_f32 v[4:5], v[8:9], v[4:5]
	v_pk_mul_f32 v[2:3], v[6:7], v[2:3]
	s_andn2_b64 vcc, exec, s[46:47]
	s_waitcnt lgkmcnt(0)
	v_mov_b32_e32 v152, v171
	v_mov_b32_e32 v153, v172
	v_mov_b32_e32 v171, v173
	v_pk_add_f32 v[152:153], v[152:153], v[170:171]
	v_mov_b32_e32 v170, v175
	v_add_f32_e32 v149, v152, v153
	v_fmamk_f32 v149, v149, 0x3a800000, v168
	v_mov_b32_e32 v171, v176
	v_mov_b32_e32 v175, v177
	v_mov_b32_e32 v172, v179
	v_mov_b32_e32 v173, v180
	v_mov_b32_e32 v179, v181
	v_mov_b32_e32 v176, v183
	v_mov_b32_e32 v177, v184
	v_mov_b32_e32 v183, v185
	v_mov_b32_e32 v180, v187
	v_mov_b32_e32 v181, v188
	v_mov_b32_e32 v187, v189
	v_mov_b32_e32 v184, v191
	v_mov_b32_e32 v185, v192
	v_mov_b32_e32 v191, v193
	v_mov_b32_e32 v188, v195
	v_mov_b32_e32 v189, v196
	v_mov_b32_e32 v195, v197
	v_rsq_f32_e32 v163, v149
	v_mov_b32_e32 v192, v199
	v_mov_b32_e32 v193, v200
	v_mov_b32_e32 v199, v201
	v_pk_add_f32 v[152:153], v[170:171], v[174:175]
	v_pk_add_f32 v[170:171], v[172:173], v[178:179]
	v_pk_add_f32 v[172:173], v[176:177], v[182:183]
	v_pk_add_f32 v[174:175], v[180:181], v[186:187]
	v_pk_add_f32 v[176:177], v[184:185], v[190:191]
	v_pk_add_f32 v[178:179], v[188:189], v[194:195]
	v_pk_add_f32 v[180:181], v[192:193], v[198:199]
	v_add_f32_e32 v151, v152, v153
	v_add_f32_e32 v152, v170, v171
	v_add_f32_e32 v153, v172, v173
	v_add_f32_e32 v155, v174, v175
	v_add_f32_e32 v157, v176, v177
	v_add_f32_e32 v159, v178, v179
	v_add_f32_e32 v161, v180, v181
	v_fmamk_f32 v149, v151, 0x3a800000, v168
	v_fmamk_f32 v151, v152, 0x3a800000, v168
	v_fmamk_f32 v152, v153, 0x3a800000, v168
	v_fmamk_f32 v153, v155, 0x3a800000, v168
	v_fmamk_f32 v155, v157, 0x3a800000, v168
	v_fmamk_f32 v157, v159, 0x3a800000, v168
	v_fmamk_f32 v159, v161, 0x3a800000, v168
	v_rsq_f32_e32 v169, v151
	v_rsq_f32_e32 v151, v157
	v_mul_f32_e32 v157, 0xbfb8aa3b, v163
	v_rsq_f32_e32 v161, v149
	v_rsq_f32_e32 v149, v159
	v_pk_mul_f32 v[174:175], v[126:127], v[156:157] op_sel:[0,1] op_sel_hi:[1,1]
	v_exp_f32_e32 v174, v174
	v_exp_f32_e32 v175, v175
	v_mul_f32_e32 v172, v163, v163
	v_pk_add_f32 v[174:175], v[174:175], v[254:255] op_sel_hi:[1,0]
	v_rcp_f32_e32 v174, v174
	v_rcp_f32_e32 v175, v175
	v_pk_mul_f32 v[128:129], v[128:129], v[156:157] op_sel:[0,1] op_sel_hi:[1,1]
	v_exp_f32_e32 v128, v128
	v_exp_f32_e32 v129, v129
	v_rsq_f32_e32 v173, v152
	v_rsq_f32_e32 v176, v153
	v_pk_add_f32 v[128:129], v[128:129], v[254:255] op_sel_hi:[1,0]
	v_rcp_f32_e32 v128, v128
	v_rcp_f32_e32 v129, v129
	v_pk_mul_f32 v[126:127], v[172:173], v[174:175] op_sel_hi:[0,1]
	v_pk_mul_f32 v[122:123], v[122:123], v[126:127]
	v_mov_b64_e32 v[152:153], s[18:19]
	v_pk_mul_f32 v[126:127], v[172:173], v[128:129] op_sel_hi:[0,1]
	v_pk_mul_f32 v[128:129], v[118:119], v[156:157] op_sel:[0,1] op_sel_hi:[1,1]
	v_exp_f32_e32 v128, v128
	v_exp_f32_e32 v129, v129
	v_pk_mul_f32 v[124:125], v[124:125], v[126:127]
	v_mad_i64_i32 v[170:171], s[28:29], v202, s70, v[152:153]
	v_pk_add_f32 v[126:127], v[128:129], v[254:255] op_sel_hi:[1,0]
	v_mul_f32_e32 v128, v120, v157
	v_mul_f32_e32 v129, v121, v157
	v_exp_f32_e32 v128, v128
	v_exp_f32_e32 v129, v129
	v_rcp_f32_e32 v126, v126
	v_rcp_f32_e32 v127, v127
	v_add_f32_e32 v120, 1.0, v128
	v_add_f32_e32 v121, 1.0, v129
	v_rcp_f32_e32 v120, v120
	v_rcp_f32_e32 v121, v121
	v_pk_mul_f32 v[118:119], v[172:173], v[126:127] op_sel_hi:[0,1]
	v_pk_mul_f32 v[118:119], v[114:115], v[118:119]
	v_rsq_f32_e32 v155, v155
	v_pk_mul_f32 v[114:115], v[172:173], v[120:121] op_sel_hi:[0,1]
	v_pk_mul_f32 v[120:121], v[116:117], v[114:115]
	v_lshlrev_b64 v[114:115], 1, v[204:205]
	v_lshl_add_u64 v[126:127], v[170:171], 0, v[114:115]
	v_cvt_pk_bf16_f32 v116, v122, v123
	v_cvt_pk_bf16_f32 v117, v124, v125
	v_cvt_pk_bf16_f32 v118, v118, v119
	v_cvt_pk_bf16_f32 v119, v120, v121
	global_store_dwordx4 v[126:127], v[116:119], off
	s_nop 1
	v_mul_f32_e32 v119, 0xbfb8aa3b, v161
	v_pk_mul_f32 v[120:121], v[110:111], v[118:119] op_sel:[0,1] op_sel_hi:[1,1]
	v_exp_f32_e32 v120, v120
	v_exp_f32_e32 v121, v121
	v_pk_mul_f32 v[122:123], v[112:113], v[118:119] op_sel:[0,1] op_sel_hi:[1,1]
	v_exp_f32_e32 v122, v122
	v_exp_f32_e32 v123, v123
	v_pk_add_f32 v[120:121], v[120:121], v[254:255] op_sel_hi:[1,0]
	v_rcp_f32_e32 v120, v120
	v_rcp_f32_e32 v121, v121
	v_pk_add_f32 v[122:123], v[122:123], v[254:255] op_sel_hi:[1,0]
	v_rcp_f32_e32 v112, v122
	v_rcp_f32_e32 v113, v123
	v_mul_f32_e32 v118, v161, v161
	v_pk_mul_f32 v[110:111], v[118:119], v[120:121] op_sel_hi:[0,1]
	v_pk_mul_f32 v[106:107], v[106:107], v[110:111]
	v_pk_mul_f32 v[110:111], v[118:119], v[112:113] op_sel_hi:[0,1]
	v_pk_mul_f32 v[112:113], v[102:103], v[118:119] op_sel:[0,1] op_sel_hi:[1,1]
	v_exp_f32_e32 v112, v112
	v_exp_f32_e32 v113, v113
	v_pk_mul_f32 v[108:109], v[108:109], v[110:111]
	v_mad_i64_i32 v[116:117], s[28:29], v162, s70, v[152:153]
	v_pk_add_f32 v[110:111], v[112:113], v[254:255] op_sel_hi:[1,0]
	v_pk_mul_f32 v[112:113], v[104:105], v[118:119] op_sel:[0,1] op_sel_hi:[1,1]
	v_exp_f32_e32 v112, v112
	v_exp_f32_e32 v113, v113
	v_rcp_f32_e32 v110, v110
	v_rcp_f32_e32 v111, v111
	v_pk_add_f32 v[112:113], v[112:113], v[254:255] op_sel_hi:[1,0]
	v_rcp_f32_e32 v104, v112
	v_rcp_f32_e32 v105, v113
	v_pk_mul_f32 v[102:103], v[118:119], v[110:111] op_sel_hi:[0,1]
	v_pk_mul_f32 v[102:103], v[98:99], v[102:103]
	v_lshl_add_u64 v[110:111], v[116:117], 0, v[114:115]
	v_pk_mul_f32 v[98:99], v[118:119], v[104:105] op_sel_hi:[0,1]
	v_pk_mul_f32 v[104:105], v[100:101], v[98:99]
	v_cvt_pk_bf16_f32 v98, v106, v107
	v_cvt_pk_bf16_f32 v99, v108, v109
	v_cvt_pk_bf16_f32 v100, v102, v103
	v_cvt_pk_bf16_f32 v101, v104, v105
	global_store_dwordx4 v[110:111], v[98:101], off
	s_nop 1
	v_mul_f32_e32 v101, 0xbfb8aa3b, v169
	v_pk_mul_f32 v[102:103], v[94:95], v[100:101] op_sel:[0,1] op_sel_hi:[1,1]
	v_exp_f32_e32 v102, v102
	v_exp_f32_e32 v103, v103
	v_pk_mul_f32 v[104:105], v[96:97], v[100:101] op_sel:[0,1] op_sel_hi:[1,1]
	v_exp_f32_e32 v104, v104
	v_exp_f32_e32 v105, v105
	v_pk_add_f32 v[102:103], v[102:103], v[254:255] op_sel_hi:[1,0]
	v_rcp_f32_e32 v102, v102
	v_rcp_f32_e32 v103, v103
	v_pk_add_f32 v[104:105], v[104:105], v[254:255] op_sel_hi:[1,0]
	v_rcp_f32_e32 v96, v104
	v_rcp_f32_e32 v97, v105
	v_mul_f32_e32 v100, v169, v169
	v_pk_mul_f32 v[94:95], v[100:101], v[102:103] op_sel_hi:[0,1]
	v_pk_mul_f32 v[90:91], v[90:91], v[94:95]
	v_pk_mul_f32 v[94:95], v[100:101], v[96:97] op_sel_hi:[0,1]
	v_pk_mul_f32 v[96:97], v[86:87], v[100:101] op_sel:[0,1] op_sel_hi:[1,1]
	v_exp_f32_e32 v96, v96
	v_exp_f32_e32 v97, v97
	v_pk_mul_f32 v[92:93], v[92:93], v[94:95]
	v_mad_i64_i32 v[98:99], s[28:29], v160, s70, v[152:153]
	v_pk_add_f32 v[94:95], v[96:97], v[254:255] op_sel_hi:[1,0]
	v_pk_mul_f32 v[96:97], v[88:89], v[100:101] op_sel:[0,1] op_sel_hi:[1,1]
	v_exp_f32_e32 v96, v96
	v_exp_f32_e32 v97, v97
	v_rcp_f32_e32 v94, v94
	v_rcp_f32_e32 v95, v95
	v_pk_add_f32 v[96:97], v[96:97], v[254:255] op_sel_hi:[1,0]
	v_rcp_f32_e32 v88, v96
	v_rcp_f32_e32 v89, v97
	v_pk_mul_f32 v[86:87], v[100:101], v[94:95] op_sel_hi:[0,1]
	v_pk_mul_f32 v[86:87], v[82:83], v[86:87]
	v_lshl_add_u64 v[94:95], v[98:99], 0, v[114:115]
	v_pk_mul_f32 v[82:83], v[100:101], v[88:89] op_sel_hi:[0,1]
	v_pk_mul_f32 v[88:89], v[84:85], v[82:83]
	v_cvt_pk_bf16_f32 v82, v90, v91
	v_cvt_pk_bf16_f32 v83, v92, v93
	v_cvt_pk_bf16_f32 v84, v86, v87
	v_cvt_pk_bf16_f32 v85, v88, v89
	global_store_dwordx4 v[94:95], v[82:85], off
	s_nop 1
	v_mul_f32_e32 v85, 0xbfb8aa3b, v173
	v_pk_mul_f32 v[86:87], v[78:79], v[84:85] op_sel:[0,1] op_sel_hi:[1,1]
	v_exp_f32_e32 v86, v86
	v_exp_f32_e32 v87, v87
	v_pk_mul_f32 v[88:89], v[80:81], v[84:85] op_sel:[0,1] op_sel_hi:[1,1]
	v_exp_f32_e32 v88, v88
	v_exp_f32_e32 v89, v89
	v_pk_add_f32 v[86:87], v[86:87], v[254:255] op_sel_hi:[1,0]
	v_rcp_f32_e32 v86, v86
	v_rcp_f32_e32 v87, v87
	v_pk_add_f32 v[88:89], v[88:89], v[254:255] op_sel_hi:[1,0]
	v_rcp_f32_e32 v80, v88
	v_rcp_f32_e32 v81, v89
	v_mul_f32_e32 v84, v173, v173
	v_pk_mul_f32 v[78:79], v[84:85], v[86:87] op_sel_hi:[0,1]
	v_pk_mul_f32 v[74:75], v[74:75], v[78:79]
	v_pk_mul_f32 v[78:79], v[84:85], v[80:81] op_sel_hi:[0,1]
	v_pk_mul_f32 v[80:81], v[70:71], v[84:85] op_sel:[0,1] op_sel_hi:[1,1]
	v_exp_f32_e32 v80, v80
	v_exp_f32_e32 v81, v81
	v_pk_mul_f32 v[76:77], v[76:77], v[78:79]
	v_mad_i64_i32 v[82:83], s[28:29], v158, s70, v[152:153]
	v_pk_add_f32 v[78:79], v[80:81], v[254:255] op_sel_hi:[1,0]
	v_pk_mul_f32 v[80:81], v[72:73], v[84:85] op_sel:[0,1] op_sel_hi:[1,1]
	v_exp_f32_e32 v80, v80
	v_exp_f32_e32 v81, v81
	v_rcp_f32_e32 v78, v78
	v_rcp_f32_e32 v79, v79
	v_pk_add_f32 v[80:81], v[80:81], v[254:255] op_sel_hi:[1,0]
	v_rcp_f32_e32 v72, v80
	v_rcp_f32_e32 v73, v81
	v_pk_mul_f32 v[70:71], v[84:85], v[78:79] op_sel_hi:[0,1]
	v_pk_mul_f32 v[70:71], v[66:67], v[70:71]
	v_lshl_add_u64 v[78:79], v[82:83], 0, v[114:115]
	v_pk_mul_f32 v[66:67], v[84:85], v[72:73] op_sel_hi:[0,1]
	v_pk_mul_f32 v[72:73], v[68:69], v[66:67]
	v_cvt_pk_bf16_f32 v66, v74, v75
	v_cvt_pk_bf16_f32 v67, v76, v77
	v_cvt_pk_bf16_f32 v68, v70, v71
	v_cvt_pk_bf16_f32 v69, v72, v73
	global_store_dwordx4 v[78:79], v[66:69], off
	s_nop 1
	v_mul_f32_e32 v69, 0xbfb8aa3b, v176
	v_pk_mul_f32 v[70:71], v[62:63], v[68:69] op_sel:[0,1] op_sel_hi:[1,1]
	v_exp_f32_e32 v70, v70
	v_exp_f32_e32 v71, v71
	v_pk_mul_f32 v[72:73], v[64:65], v[68:69] op_sel:[0,1] op_sel_hi:[1,1]
	v_exp_f32_e32 v72, v72
	v_exp_f32_e32 v73, v73
	v_pk_add_f32 v[70:71], v[70:71], v[254:255] op_sel_hi:[1,0]
	v_rcp_f32_e32 v70, v70
	v_rcp_f32_e32 v71, v71
	v_pk_add_f32 v[72:73], v[72:73], v[254:255] op_sel_hi:[1,0]
	v_rcp_f32_e32 v64, v72
	v_rcp_f32_e32 v65, v73
	v_mul_f32_e32 v68, v176, v176
	v_pk_mul_f32 v[62:63], v[68:69], v[70:71] op_sel_hi:[0,1]
	v_pk_mul_f32 v[58:59], v[58:59], v[62:63]
	v_pk_mul_f32 v[62:63], v[68:69], v[64:65] op_sel_hi:[0,1]
	v_pk_mul_f32 v[64:65], v[54:55], v[68:69] op_sel:[0,1] op_sel_hi:[1,1]
	v_exp_f32_e32 v64, v64
	v_exp_f32_e32 v65, v65
	v_pk_mul_f32 v[60:61], v[60:61], v[62:63]
	v_mad_i64_i32 v[66:67], s[28:29], v156, s70, v[152:153]
	v_pk_add_f32 v[62:63], v[64:65], v[254:255] op_sel_hi:[1,0]
	v_pk_mul_f32 v[64:65], v[56:57], v[68:69] op_sel:[0,1] op_sel_hi:[1,1]
	v_exp_f32_e32 v64, v64
	v_exp_f32_e32 v65, v65
	v_rcp_f32_e32 v62, v62
	v_rcp_f32_e32 v63, v63
	v_pk_add_f32 v[64:65], v[64:65], v[254:255] op_sel_hi:[1,0]
	v_rcp_f32_e32 v56, v64
	v_rcp_f32_e32 v57, v65
	v_pk_mul_f32 v[54:55], v[68:69], v[62:63] op_sel_hi:[0,1]
	v_pk_mul_f32 v[54:55], v[50:51], v[54:55]
	v_lshl_add_u64 v[62:63], v[66:67], 0, v[114:115]
	v_pk_mul_f32 v[50:51], v[68:69], v[56:57] op_sel_hi:[0,1]
	v_pk_mul_f32 v[56:57], v[52:53], v[50:51]
	v_cvt_pk_bf16_f32 v50, v58, v59
	v_cvt_pk_bf16_f32 v51, v60, v61
	v_cvt_pk_bf16_f32 v52, v54, v55
	v_cvt_pk_bf16_f32 v53, v56, v57
	global_store_dwordx4 v[62:63], v[50:53], off
	s_nop 1
	v_mul_f32_e32 v53, 0xbfb8aa3b, v155
	v_pk_mul_f32 v[54:55], v[46:47], v[52:53] op_sel:[0,1] op_sel_hi:[1,1]
	v_exp_f32_e32 v54, v54
	v_exp_f32_e32 v55, v55
	v_pk_mul_f32 v[56:57], v[48:49], v[52:53] op_sel:[0,1] op_sel_hi:[1,1]
	v_exp_f32_e32 v56, v56
	v_exp_f32_e32 v57, v57
	v_pk_add_f32 v[54:55], v[54:55], v[254:255] op_sel_hi:[1,0]
	v_rcp_f32_e32 v54, v54
	v_rcp_f32_e32 v55, v55
	v_pk_add_f32 v[56:57], v[56:57], v[254:255] op_sel_hi:[1,0]
	v_rcp_f32_e32 v48, v56
	v_rcp_f32_e32 v49, v57
	v_mul_f32_e32 v52, v155, v155
	v_pk_mul_f32 v[46:47], v[52:53], v[54:55] op_sel_hi:[0,1]
	v_pk_mul_f32 v[42:43], v[42:43], v[46:47]
	v_pk_mul_f32 v[46:47], v[52:53], v[48:49] op_sel_hi:[0,1]
	v_pk_mul_f32 v[48:49], v[38:39], v[52:53] op_sel:[0,1] op_sel_hi:[1,1]
	v_exp_f32_e32 v48, v48
	v_exp_f32_e32 v49, v49
	v_pk_mul_f32 v[44:45], v[44:45], v[46:47]
	v_mad_i64_i32 v[50:51], s[28:29], v154, s70, v[152:153]
	v_pk_add_f32 v[46:47], v[48:49], v[254:255] op_sel_hi:[1,0]
	v_pk_mul_f32 v[48:49], v[40:41], v[52:53] op_sel:[0,1] op_sel_hi:[1,1]
	v_exp_f32_e32 v48, v48
	v_exp_f32_e32 v49, v49
	v_rcp_f32_e32 v46, v46
	v_rcp_f32_e32 v47, v47
	v_pk_add_f32 v[48:49], v[48:49], v[254:255] op_sel_hi:[1,0]
	v_rcp_f32_e32 v40, v48
	v_rcp_f32_e32 v41, v49
	v_pk_mul_f32 v[38:39], v[52:53], v[46:47] op_sel_hi:[0,1]
	v_pk_mul_f32 v[38:39], v[34:35], v[38:39]
	v_lshl_add_u64 v[46:47], v[50:51], 0, v[114:115]
	v_pk_mul_f32 v[34:35], v[52:53], v[40:41] op_sel_hi:[0,1]
	v_pk_mul_f32 v[40:41], v[36:37], v[34:35]
	v_cvt_pk_bf16_f32 v34, v42, v43
	v_cvt_pk_bf16_f32 v35, v44, v45
	v_cvt_pk_bf16_f32 v36, v38, v39
	v_cvt_pk_bf16_f32 v37, v40, v41
	global_store_dwordx4 v[46:47], v[34:37], off
	s_nop 1
	v_mul_f32_e32 v37, 0xbfb8aa3b, v151
	v_pk_mul_f32 v[38:39], v[30:31], v[36:37] op_sel:[0,1] op_sel_hi:[1,1]
	v_exp_f32_e32 v38, v38
	v_exp_f32_e32 v39, v39
	v_pk_mul_f32 v[40:41], v[32:33], v[36:37] op_sel:[0,1] op_sel_hi:[1,1]
	v_exp_f32_e32 v40, v40
	v_exp_f32_e32 v41, v41
	v_pk_add_f32 v[38:39], v[38:39], v[254:255] op_sel_hi:[1,0]
	v_rcp_f32_e32 v38, v38
	v_rcp_f32_e32 v39, v39
	v_pk_add_f32 v[40:41], v[40:41], v[254:255] op_sel_hi:[1,0]
	v_rcp_f32_e32 v32, v40
	v_rcp_f32_e32 v33, v41
	v_mul_f32_e32 v36, v151, v151
	v_pk_mul_f32 v[30:31], v[36:37], v[38:39] op_sel_hi:[0,1]
	v_pk_mul_f32 v[26:27], v[26:27], v[30:31]
	v_pk_mul_f32 v[30:31], v[36:37], v[32:33] op_sel_hi:[0,1]
	v_pk_mul_f32 v[32:33], v[22:23], v[36:37] op_sel:[0,1] op_sel_hi:[1,1]
	v_exp_f32_e32 v32, v32
	v_exp_f32_e32 v33, v33
	v_pk_mul_f32 v[28:29], v[28:29], v[30:31]
	v_mad_i64_i32 v[34:35], s[28:29], v150, s70, v[152:153]
	v_pk_add_f32 v[30:31], v[32:33], v[254:255] op_sel_hi:[1,0]
	v_pk_mul_f32 v[32:33], v[24:25], v[36:37] op_sel:[0,1] op_sel_hi:[1,1]
	v_exp_f32_e32 v32, v32
	v_exp_f32_e32 v33, v33
	v_rcp_f32_e32 v30, v30
	v_rcp_f32_e32 v31, v31
	v_pk_add_f32 v[32:33], v[32:33], v[254:255] op_sel_hi:[1,0]
	v_rcp_f32_e32 v24, v32
	v_rcp_f32_e32 v25, v33
	v_pk_mul_f32 v[22:23], v[36:37], v[30:31] op_sel_hi:[0,1]
	v_pk_mul_f32 v[22:23], v[18:19], v[22:23]
	v_lshl_add_u64 v[30:31], v[34:35], 0, v[114:115]
	v_pk_mul_f32 v[18:19], v[36:37], v[24:25] op_sel_hi:[0,1]
	v_pk_mul_f32 v[24:25], v[20:21], v[18:19]
	v_cvt_pk_bf16_f32 v18, v26, v27
	v_cvt_pk_bf16_f32 v19, v28, v29
	v_cvt_pk_bf16_f32 v20, v22, v23
	v_cvt_pk_bf16_f32 v21, v24, v25
	global_store_dwordx4 v[30:31], v[18:21], off
	s_nop 1
	v_mul_f32_e32 v21, 0xbfb8aa3b, v149
	v_pk_mul_f32 v[22:23], v[14:15], v[20:21] op_sel:[0,1] op_sel_hi:[1,1]
	v_exp_f32_e32 v22, v22
	v_exp_f32_e32 v23, v23
	v_pk_mul_f32 v[24:25], v[16:17], v[20:21] op_sel:[0,1] op_sel_hi:[1,1]
	v_exp_f32_e32 v24, v24
	v_exp_f32_e32 v25, v25
	v_pk_add_f32 v[22:23], v[22:23], v[254:255] op_sel_hi:[1,0]
	v_rcp_f32_e32 v22, v22
	v_rcp_f32_e32 v23, v23
	v_pk_add_f32 v[24:25], v[24:25], v[254:255] op_sel_hi:[1,0]
	v_rcp_f32_e32 v16, v24
	v_rcp_f32_e32 v17, v25
	v_mul_f32_e32 v20, v149, v149
	v_pk_mul_f32 v[14:15], v[20:21], v[22:23] op_sel_hi:[0,1]
	v_pk_mul_f32 v[10:11], v[10:11], v[14:15]
	v_pk_mul_f32 v[14:15], v[20:21], v[16:17] op_sel_hi:[0,1]
	v_pk_mul_f32 v[16:17], v[6:7], v[20:21] op_sel:[0,1] op_sel_hi:[1,1]
	v_exp_f32_e32 v16, v16
	v_exp_f32_e32 v17, v17
	v_pk_mul_f32 v[12:13], v[12:13], v[14:15]
	v_mad_i64_i32 v[18:19], s[28:29], v148, s70, v[152:153]
	v_pk_add_f32 v[14:15], v[16:17], v[254:255] op_sel_hi:[1,0]
	v_pk_mul_f32 v[16:17], v[8:9], v[20:21] op_sel:[0,1] op_sel_hi:[1,1]
	v_exp_f32_e32 v16, v16
	v_exp_f32_e32 v17, v17
	v_rcp_f32_e32 v14, v14
	v_rcp_f32_e32 v15, v15
	v_pk_add_f32 v[16:17], v[16:17], v[254:255] op_sel_hi:[1,0]
	v_rcp_f32_e32 v8, v16
	v_rcp_f32_e32 v9, v17
	v_pk_mul_f32 v[6:7], v[20:21], v[14:15] op_sel_hi:[0,1]
	v_pk_mul_f32 v[6:7], v[2:3], v[6:7]
	v_lshl_add_u64 v[14:15], v[18:19], 0, v[114:115]
	v_pk_mul_f32 v[2:3], v[20:21], v[8:9] op_sel_hi:[0,1]
	v_pk_mul_f32 v[8:9], v[4:5], v[2:3]
	v_cvt_pk_bf16_f32 v2, v10, v11
	v_cvt_pk_bf16_f32 v3, v12, v13
	v_cvt_pk_bf16_f32 v4, v6, v7
	v_cvt_pk_bf16_f32 v5, v8, v9
	global_store_dwordx4 v[14:15], v[2:5], off
	s_cbranch_vccnz .LBB0_1929
	s_ashr_i32 s14, s14, 2
	s_cmp_lt_i32 s14, 4
	s_cbranch_scc1 .LBB0_1929
	s_waitcnt vmcnt(0)
	s_and_saveexec_b64 s[28:29], s[2:3]
	s_cbranch_execz .LBB0_1928
	s_mov_b64 s[30:31], exec
	v_mbcnt_lo_u32_b32 v2, s30, 0
	v_mbcnt_hi_u32_b32 v2, s31, v2
	v_cmp_eq_u32_e32 vcc, 0, v2
	s_and_b64 s[58:59], exec, vcc
	s_mov_b64 exec, s[58:59]
	s_cbranch_execz .LBB0_1928
	s_lshl_b32 s14, s14, 6
	s_addk_i32 s14, 0xff00
	s_lshl_b64 s[58:59], s[14:15], 2
	s_add_u32 s58, s38, s58
	s_addc_u32 s59, s39, s59
	s_bcnt1_i32_b64 s14, s[30:31]
	v_mov_b32_e32 v2, s14
	global_atomic_add v133, v2, s[58:59]

	.amdhsa_kernel _Z6mk_fwd4Args
		.amdhsa_group_segment_fixed_size 0
		.amdhsa_private_segment_fixed_size 0
		.amdhsa_kernarg_size 416
		.amdhsa_user_sgpr_count 2
		.amdhsa_user_sgpr_dispatch_ptr 0
		.amdhsa_user_sgpr_queue_ptr 0
		.amdhsa_user_sgpr_kernarg_segment_ptr 1
		.amdhsa_user_sgpr_dispatch_id 0
		.amdhsa_user_sgpr_kernarg_preload_length 0
		.amdhsa_user_sgpr_kernarg_preload_offset 0
		.amdhsa_user_sgpr_private_segment_size 0
		.amdhsa_uses_dynamic_stack 0
		.amdhsa_enable_private_segment 0
		.amdhsa_system_sgpr_workgroup_id_x 1
		.amdhsa_system_sgpr_workgroup_id_y 0
		.amdhsa_system_sgpr_workgroup_id_z 0
		.amdhsa_system_sgpr_workgroup_info 0
		.amdhsa_system_vgpr_workitem_id 0
		.amdhsa_next_free_vgpr 256
		.amdhsa_next_free_sgpr 102
		.amdhsa_accum_offset 256
		.amdhsa_reserve_vcc 1
		.amdhsa_float_round_mode_32 0
		.amdhsa_float_round_mode_16_64 0
		.amdhsa_float_denorm_mode_32 3
		.amdhsa_float_denorm_mode_16_64 3
		.amdhsa_dx10_clamp 1
		.amdhsa_ieee_mode 1
		.amdhsa_fp16_overflow 0
		.amdhsa_tg_split 0
		.amdhsa_exception_fp_ieee_invalid_op 0
		.amdhsa_exception_fp_denorm_src 0
		.amdhsa_exception_fp_ieee_div_zero 0
		.amdhsa_exception_fp_ieee_overflow 0
		.amdhsa_exception_fp_ieee_underflow 0
		.amdhsa_exception_fp_ieee_inexact 0
		.amdhsa_exception_int_div_zero 0
	.end_amdhsa_kernel

amdhsa.kernels:
  - .agpr_count:     0
    .args:
      - .offset:         0
        .size:           160
        .value_kind:     by_value
      - .offset:         160
        .size:           4
        .value_kind:     hidden_block_count_x
      - .offset:         164
        .size:           4
        .value_kind:     hidden_block_count_y
      - .offset:         168
        .size:           4
        .value_kind:     hidden_block_count_z
      - .offset:         172
        .size:           2
        .value_kind:     hidden_group_size_x
      - .offset:         174
        .size:           2
        .value_kind:     hidden_group_size_y
      - .offset:         176
        .size:           2
        .value_kind:     hidden_group_size_z
      - .offset:         178
        .size:           2
        .value_kind:     hidden_remainder_x
      - .offset:         180
        .size:           2
        .value_kind:     hidden_remainder_y
      - .offset:         182
        .size:           2
        .value_kind:     hidden_remainder_z
      - .offset:         200
        .size:           8
        .value_kind:     hidden_global_offset_x
      - .offset:         208
        .size:           8
        .value_kind:     hidden_global_offset_y
      - .offset:         216
        .size:           8
        .value_kind:     hidden_global_offset_z
      - .offset:         224
        .size:           2
        .value_kind:     hidden_grid_dims
      - .offset:         280
        .size:           4
        .value_kind:     hidden_dynamic_lds_size
    .group_segment_fixed_size: 0
    .kernarg_segment_align: 8
    .kernarg_segment_size: 416
    .language:       OpenCL C
    .language_version:
      - 2
      - 0
    .max_flat_workgroup_size: 512
    .name:           _Z6mk_fwd4Args
    .private_segment_fixed_size: 0
    .sgpr_count:     108
    .sgpr_spill_count: 50
    .symbol:         _Z6mk_fwd4Args.kd
    .uniform_work_group_size: 1
    .uses_dynamic_stack: false
    .vgpr_count:     256
    .vgpr_spill_count: 0
    .wavefront_size: 64
